# vp56 plus 4-byte shift of the P8 epilogue only (K-loop placement unchanged)
# speedup vs baseline: 1.0040x; 1.0016x over previous
; __device__ __forceinline__ float sigmoidf_(float x) { return __builtin_amdgcn_rcpf(1.0f + __builtin_amdgcn_exp2f(-LOG2E * x)); }
; __device__ __forceinline__ u32x4v pack8(const f32x4 a, const f32x4 b) { u32x4v w; w.x = pkbf(a[0], a[1]); w.y = pkbf(a[2], a[3]); w.z = pkbf(b[0], b[1]); w.w = pkbf(b[2], b[3]); return w; }
; __device__ __forceinline__ unsigned pk4_fp8(float a, float b, float cc, float d) { int w = 0; w = __builtin_amdgcn_cvt_pk_fp8_f32(a, b, w, false); w = __builtin_amdgcn_cvt_pk_fp8_f32(cc, d, w, true); return (unsigned)w; }
;     __device__ __forceinline__ void operator()(const pg8::f32x4 (&acc)[2][2][4][2], const Unit& u, int wr, int wc, int fr, int fq) const {
;         const int row0 = u.pm * BM + wr * 64 + fr; const int col0 = u.pn * HALF + wc * 32 + 8 * fq; const bool f8 = (u.pn * HALF) < h8;
; #pragma unroll
;         for (int ai = 0; ai < 2; ++ai)
; #pragma unroll
;             for (int m = 0; m < 4; ++m) { pg8::f32x4 g0 = acc[ai][0][m][0], g1 = acc[ai][0][m][1]; const pg8::f32x4 u0 = acc[ai][1][m][0], u1 = acc[ai][1][m][1];
; #pragma unroll
;                 for (int e = 0; e < 4; ++e) { g0[e] = g0[e] * sigmoidf_(g0[e]) * u0[e]; g1[e] = g1[e] * sigmoidf_(g1[e]) * u1[e]; }
;                 unsigned char* rowp = O + (size_t)(row0 + ai * HALF + m * 16) * pitch;
;                 if (f8) { u32x2v o; o.x = pk4_fp8(g0[0] * s8, g0[1] * s8, g0[2] * s8, g0[3] * s8); o.y = pk4_fp8(g1[0] * s8, g1[1] * s8, g1[2] * s8, g1[3] * s8); *(u32x2v*)(rowp + col0) = o; }
;                 else *(u32x4v*)(rowp + h8 + 2 * (col0 - h8)) = pack8(g0, g1); }
;     }
.LBB0_726:
	s_nop 0
	v_mul_f32_e32 v145, 0xbfb8aa3b, v124
	v_exp_f32_e32 v145, v145
	v_mul_f32_e32 v154, 0xbfb8aa3b, v120
	v_exp_f32_e32 v154, v154
	v_lshl_add_u32 v153, s26, 8, v146
	v_add_f32_e32 v145, 1.0, v145
	v_rcp_f32_e32 v155, v145
	v_add_f32_e32 v145, 1.0, v154
	v_rcp_f32_e32 v154, v145
	s_cmp_gt_i32 s8, 11
	v_mul_f32_e32 v124, v124, v155
	v_mul_f32_e32 v116, v124, v116
	v_mul_f32_e32 v124, 0xbfb8aa3b, v125
	v_mul_f32_e32 v120, v120, v154
	v_exp_f32_e32 v124, v124
	v_mul_f32_e32 v154, 0xbfb8aa3b, v121
	v_exp_f32_e32 v154, v154
	v_mul_f32_e32 v120, v120, v112
	v_add_f32_e32 v112, 1.0, v124
	v_rcp_f32_e32 v112, v112
	v_add_f32_e32 v124, 1.0, v154
	v_mul_f32_e32 v154, 0xbfb8aa3b, v126
	v_rcp_f32_e32 v124, v124
	v_exp_f32_e32 v154, v154
	v_mul_f32_e32 v112, v125, v112
	v_mul_f32_e32 v117, v112, v117
	v_mul_f32_e32 v112, v121, v124
	v_add_f32_e32 v121, 1.0, v154
	v_rcp_f32_e32 v124, v121
	v_mul_f32_e32 v121, 0xbfb8aa3b, v122
	v_exp_f32_e32 v125, v121
	v_mul_f32_e32 v121, v112, v113
	v_mul_f32_e32 v112, v126, v124
	v_mul_f32_e32 v113, 0xbfb8aa3b, v127
	v_mul_f32_e32 v118, v112, v118
	v_add_f32_e32 v112, 1.0, v125
	v_exp_f32_e32 v113, v113
	v_mul_f32_e32 v124, 0xbfb8aa3b, v123
	v_rcp_f32_e32 v112, v112
	v_exp_f32_e32 v124, v124
	v_add_f32_e32 v113, 1.0, v113
	v_rcp_f32_e32 v113, v113
	v_mul_f32_e32 v112, v122, v112
	v_add_f32_e32 v122, 1.0, v124
	v_rcp_f32_e32 v125, v122
	v_mul_f32_e32 v122, v112, v114
	v_mul_f32_e32 v112, v127, v113
	v_mul_f32_e32 v124, v112, v119
	v_mul_f32_e32 v112, v123, v125
	v_mul_f32_e32 v119, v112, v115
	v_mov_b64_e32 v[112:113], s[12:13]
	v_lshl_or_b32 v144, s8, 7, v148
	s_cselect_b64 s[26:27], -1, 0
	v_mad_i64_i32 v[114:115], s[8:9], v153, s58, v[112:113]
	v_ashrrev_i32_e32 v145, 31, v144
	s_mov_b64 s[8:9], -1
	s_and_b64 vcc, exec, s[26:27]
	v_lshl_add_u32 v112, v144, 1, v152
	s_cbranch_vccz .LBB0_728
	v_ashrrev_i32_e32 v113, 31, v112
	v_lshl_add_u64 v[126:127], v[114:115], 0, v[112:113]
	v_cvt_pk_bf16_f32 v154, v116, v117
	v_cvt_pk_bf16_f32 v155, v118, v124
	v_cvt_pk_bf16_f32 v156, v120, v121
	v_cvt_pk_bf16_f32 v157, v122, v119
	global_store_dwordx4 v[126:127], v[154:157], off offset:1536
	s_mov_b64 s[8:9], 0
